# adds: NSA top-16 rank-count loop uses rotating SGPR-pair carries (no s_nop); decode-cache block-mean items moved out of phase 0 and run at block-dependent GEMM1 tile boundaries (overlaps HBM streaming
# speedup vs baseline: 1.0532x; 1.0066x over previous
; DI int opaque(int v) { asm volatile("" : "+v"(v)); return v; }
; DI void kmean_item(const float* __restrict__ base, const int* __restrict__ pt, int b, int n, float* __restrict__ outp, char* sm) {
;     float* scr = (float*)sm;
;     const int t = opaque(threadIdx.x), lane = t & 63, w = t >> 6;
;     f32x4 a0 = {0.f, 0.f, 0.f, 0.f}, a1 = {0.f, 0.f, 0.f, 0.f};
; #pragma unroll
;     for (int hf = 0; hf < 2; ++hf) {
;         const int pos0 = n * 256 + hf * 128;
;         const size_t r0 = pt ? (size_t)pt[b * 64 + (pos0 >> 7)] * 128 : (size_t)b * 8192 + pos0;
;         const float* rp = base + (r0 + w) * 1024 + lane * 4;
; #pragma unroll 4
;         for (int rr = 0; rr < 32; ++rr) {
;             a0 += __builtin_nontemporal_load((const f32x4*)(rp + (size_t)rr * 4096));
;             a1 += __builtin_nontemporal_load((const f32x4*)(rp + (size_t)rr * 4096 + 256));
;         }
;     }
;     *(f32x4*)(scr + w * 512 + lane * 4) = a0;
;     *(f32x4*)(scr + w * 512 + 256 + lane * 4) = a1;
;     __syncthreads();
; #pragma unroll
;     for (int j = 0; j < 2; ++j) {
;         const int col = t + 256 * j;
;         outp[col] = (scr[col] + scr[512 + col] + scr[1024 + col] + scr[1536 + col]) * (1.f / 256.f);
;     }
;     __syncthreads();
; }
;     ...
;         if (r < P0_KMS) { if (msk & 2) kmean_item(p.cache_m, p.page_table, r >> 5, r & 31, (float*)(p.ws + WS_KMS) + (size_t)r * 512, sm); continue; } r -= P0_KMS;
.LBB0_93:
	s_andn2_b64 vcc, exec, s[2:3]
	s_cbranch_vccnz .LBB0_105
.LBB0_105:
	s_cbranch_execnz .LBB0_8

;     ...
;         const int x = blockIdx.x & 7, ntn = x < 7 ? 4 : 3, nb = gridDim.x >> 3, j = blockIdx.x >> 3;
;         const int lim = 128 * ntn, nown = j < lim ? (lim - j + nb - 1) / nb : 0;
;         auto tile_at = [&](int idx, int& tm, int& tn) -> bool {
;             if (idx < nown) { const int s2 = j + idx * nb; tm = s2 / ntn; tn = 4 * x + s2 % ntn; return true; }
;             const int e = j + (idx - nown) * nb;
;             tm = 128; tn = e;
;             return x == 7 && e < 31;
;         };
;         GemmRegs<ALoadBf16> G; bool pre = false;
;         int tm = 0, tn = 0;
;         bool have = tile_at(0, tm, tn);
.LBB0_252:
	s_mov_b32 s98, 0
	s_load_dword s3, s[34:35], 0x10
	s_and_b32 s8, s80, 7
	s_cmp_eq_u32 s8, 7
	s_cselect_b64 s[4:5], -1, 0
	s_and_b64 s[0:1], s[4:5], exec
	s_cselect_b32 s31, 3, 4
	s_waitcnt lgkmcnt(0)
	s_lshr_b32 s0, s3, 16
	s_cmp_lg_u32 s0, 0
	s_cselect_b64 s[0:1], -1, 0
	s_cmp_lg_u64 s[0:1], 0
	s_addc_u32 s0, s2, 0
	s_lshr_b32 s33, s0, 3
	s_lshr_b32 s30, s80, 3
	s_lshl_b32 s0, s31, 7
	s_cmp_ge_u32 s30, s0
	s_mov_b32 s68, 0
	s_cbranch_scc1 .LBB0_254
	v_cvt_f32_u32_e32 v2, s33
	s_not_b32 s1, s30
	s_sub_i32 s2, 0, s33
	s_add_i32 s0, s0, s1
	v_rcp_iflag_f32_e32 v2, v2
	s_add_i32 s0, s0, s33
	s_ashr_i32 s1, s0, 31
	s_abs_i32 s0, s0
	v_mul_f32_e32 v2, 0x4f7ffffe, v2
	v_cvt_u32_f32_e32 v2, v2
	s_nop 0
	v_readfirstlane_b32 s3, v2
	s_mul_i32 s2, s2, s3
	s_mul_hi_u32 s2, s3, s2
	s_add_i32 s3, s3, s2
	s_mul_hi_u32 s2, s0, s3
	s_mul_i32 s3, s2, s33
	s_sub_i32 s0, s0, s3
	s_add_i32 s9, s2, 1
	s_sub_i32 s3, s0, s33
	s_cmp_ge_u32 s0, s33
	s_cselect_b32 s2, s9, s2
	s_cselect_b32 s0, s3, s0
	s_add_i32 s3, s2, 1
	s_cmp_ge_u32 s0, s33
	s_cselect_b32 s0, s3, s2
	s_xor_b32 s0, s0, s1
	s_sub_i32 s68, s0, s1

; template <class AL>
; DI void gemm_mainloop(f32x16 (&acc)[2][2], GemmRegs<AL>& G, bool pre, const AL& al, const u16* __restrict__ Bt, int ldb, int n0, int nk, char* sm,
;                       bool has_next, const AL& aln, int n0n) {
;     const int t = opaque(threadIdx.x), lane = t & 63, w = t >> 6;
;     const int wm = w >> 1, wn = w & 1, r = lane & 31, h = lane >> 5;
;     const int lrow = t >> 3, lch = t & 7;
;     typename AL::Raw& RA0 = G.RA0; typename AL::Raw& RA1 = G.RA1;
;     bf16x8 (&RB0)[4] = G.RB0; bf16x8 (&RB1)[4] = G.RB1;
;     const u16* bp = Bt + (size_t)(n0 + lrow) * ldb + lch * 8;
;     const u16* bpn = Bt + (size_t)(n0n + lrow) * ldb + lch * 8;
;     auto loadB = [&](bf16x8 (&rb)[4], int kt) {
; #pragma unroll
;         for (int i = 0; i < 4; ++i) rb[i] = *(const bf16x8*)(bp + (size_t)(32 * i) * ldb + kt * 64);
;     };
;     auto loadBn = [&](bf16x8 (&rb)[4], int kt) {
; #pragma unroll
;         for (int i = 0; i < 4; ++i) rb[i] = *(const bf16x8*)(bpn + (size_t)(32 * i) * ldb + kt * 64);
;     };
;     auto store = [&](const typename AL::Raw& RA, const bf16x8 (&rb)[4], int kt, char* dA) {
;         bf16x8 ra[4];
;         al.cvt(RA, ra, AL::kmap(kt));
; #pragma unroll
;         for (int i = 0; i < 4; ++i) {
;             const int row = lrow + 32 * i;
;             const int off = row * 128 + ((lch ^ ((row >> 1) & 7)) << 4);
;             *(bf16x8*)(dA + off) = ra[i];
;             *(bf16x8*)(dA + 16384 + off) = rb[i];
;         }
;     };
;     auto compute = [&](const char* cA) {
;         const char* cB = cA + 16384;
;         bf16x8 a[2][2], b[2][2];
;         auto rd = [&](int set, int ks) {
; #pragma unroll
;             for (int mi = 0; mi < 2; ++mi) { const int row = wm * 64 + mi * 32 + r; a[set][mi] = *(const bf16x8*)(cA + row * 128 + (((2 * ks + h) ^ ((row >> 1) & 7)) << 4)); }
; #pragma unroll
;             for (int ni = 0; ni < 2; ++ni) { const int row = wn * 64 + ni * 32 + r; b[set][ni] = *(const bf16x8*)(cB + row * 128 + (((2 * ks + h) ^ ((row >> 1) & 7)) << 4)); }
;         };
;         auto mm = [&](int set) {
; #pragma unroll
;     ...
;         for (int idx = 0; have; ++idx) {
;             int tmn = 0, tnn = 0;
;             const bool hn = tile_at(idx + 1, tmn, tnn);
;             gemm1_tile(p, G, pre, tm, tn, hn, tmn, tnn, sm);
;             pre = hn; have = hn; tm = tmn; tn = tnn;
.LBB0_266:
	v_readlane_b32 s58, v254, 8
	s_nop 3
	s_lshr_b32 s56, s58, 3
	s_mul_hi_u32 s57, s56, 0x2aaaaaab
	s_mul_i32 s57, s57, 6
	s_sub_i32 s56, s56, s57
	s_mov_b32 s59, s58
	s_cmp_eq_u32 s98, s56
	s_cbranch_scc1 .Lkm3_item
	s_add_i32 s56, s56, 3
	s_add_i32 s57, s56, -6
	s_cmp_lt_u32 s56, 6
	s_cselect_b32 s56, s56, s57
	s_add_i32 s59, s58, 0x200
	s_cmp_eq_u32 s98, s56
	s_cbranch_scc1 .Lkm3_item
.Lkm3_ret:
	s_add_i32 s98, s98, 1
	s_lshl_b32 s52, s95, 7
	s_lshl_b32 s16, s42, 7
	s_xor_b64 s[54:55], s[0:1], -1
	s_cmp_lg_u64 s[2:3], 0
	s_cselect_b32 s53, 0x80, 0
	s_lshl_b32 s26, s16, 11
	s_add_u32 s26, s26, s53
	s_add_u32 s2, s6, s26
	s_addc_u32 s3, s7, 0
	s_lshl_b32 s26, s52, 11
	s_add_u32 s26, s26, s53
	s_add_u32 s64, s8, s26
	s_addc_u32 s65, s9, 0
	v_lshrrev_b32_e32 v148, 6, v0
	v_and_b32_e32 v140, 63, v0
	v_readfirstlane_b32 s17, v148
	v_lshrrev_b32_e32 v141, 3, v140
	v_and_b32_e32 v142, 7, v140
	v_lshrrev_b32_e32 v143, 1, v141
	v_xor_b32_e32 v144, v142, v143
	v_xor_b32_e32 v145, 4, v144
	v_lshl_add_u32 v146, v148, 5, v141
	v_lshlrev_b32_e32 v147, 11, v146
	v_lshl_add_u32 v136, v144, 4, v147
	v_lshl_add_u32 v137, v145, 4, v147
	v_add_u32_e32 v137, 0x3c00, v137
	v_add_u32_e32 v138, 0x7800, v136
	v_add_u32_e32 v139, 0x7800, v137
	s_lshl_b32 s56, s17, 12
	s_add_i32 s57, s56, 0x4000
	s_add_i32 s58, s56, 0x8000
	s_add_i32 s59, s56, 0xc000
	s_cmp_lg_u32 s53, 0
	s_cbranch_scc1 .Lg1_pre
	s_mov_b32 m0, s56
	s_nop 0
	global_load_lds_dwordx4 v136, s[2:3]
	global_load_lds_dwordx4 v137, s[2:3] offset:1024
	global_load_lds_dwordx4 v138, s[2:3] offset:2048
	global_load_lds_dwordx4 v139, s[2:3] offset:3072
	s_add_u32 s2, s2, 0x80
	s_addc_u32 s3, s3, 0
	s_mov_b32 m0, s57
	s_nop 0
	global_load_lds_dwordx4 v136, s[64:65]
	global_load_lds_dwordx4 v137, s[64:65] offset:1024
	global_load_lds_dwordx4 v138, s[64:65] offset:2048
	global_load_lds_dwordx4 v139, s[64:65] offset:3072
	s_add_u32 s64, s64, 0x80
	s_addc_u32 s65, s65, 0

; DI int opaque(int v) { asm volatile("" : "+v"(v)); return v; }
; DI void kmean_item(const float* __restrict__ base, const int* __restrict__ pt, int b, int n, float* __restrict__ outp, char* sm) {
;     float* scr = (float*)sm;
;     const int t = opaque(threadIdx.x), lane = t & 63, w = t >> 6;
;     f32x4 a0 = {0.f, 0.f, 0.f, 0.f}, a1 = {0.f, 0.f, 0.f, 0.f};
; #pragma unroll
;     for (int hf = 0; hf < 2; ++hf) {
;         const int pos0 = n * 256 + hf * 128;
;         const size_t r0 = pt ? (size_t)pt[b * 64 + (pos0 >> 7)] * 128 : (size_t)b * 8192 + pos0;
;         const float* rp = base + (r0 + w) * 1024 + lane * 4;
; #pragma unroll 4
;         for (int rr = 0; rr < 32; ++rr) {
;             a0 += __builtin_nontemporal_load((const f32x4*)(rp + (size_t)rr * 4096));
;             a1 += __builtin_nontemporal_load((const f32x4*)(rp + (size_t)rr * 4096 + 256));
;         }
.Lkm3_item:
	s_lshr_b32 s57, s59, 5
	s_and_b32 s58, s59, 31
	s_lshl_b32 s56, s57, 6
	s_lshl_b32 s64, s58, 1
	s_or_b32 s64, s56, s64
	s_lshl_b32 s64, s64, 2
	s_add_u32 s64, s50, s64
	s_addc_u32 s65, s51, 0
	v_mov_b32_e32 v19, 0
	global_load_dwordx2 v[2:3], v19, s[64:65]
	v_ashrrev_i32_e32 v12, 6, v0
	v_lshlrev_b32_e32 v11, 2, v0
	v_and_b32_e32 v11, 0xfc, v11
	v_lshlrev_b32_e32 v18, 2, v11
	s_waitcnt vmcnt(0)
	v_lshlrev_b32_e32 v2, 7, v2
	v_lshlrev_b32_e32 v3, 7, v3
	v_add_lshl_u32 v2, v2, v12, 12
	v_add_lshl_u32 v3, v3, v12, 12
	v_add_u32_e32 v172, v2, v18
	v_add_u32_e32 v176, v3, v18
	v_add_u32_e32 v173, 0x4000, v172
	v_add_u32_e32 v177, 0x4000, v176
	v_add_u32_e32 v174, 0x8000, v172
	v_add_u32_e32 v178, 0x8000, v176
	v_add_u32_e32 v175, 0xc000, v172
	v_add_u32_e32 v179, 0xc000, v176
	v_mov_b32_e32 v2, 0
	v_mov_b32_e32 v3, v2
	v_mov_b32_e32 v4, v2
	v_mov_b32_e32 v5, v2
	v_mov_b32_e32 v6, v2
	v_mov_b32_e32 v7, v2
	v_mov_b32_e32 v8, v2
	v_mov_b32_e32 v9, v2
	s_mov_b64 s[66:67], s[44:45]
	global_load_dwordx4 v[26:29], v172, s[66:67] nt
	global_load_dwordx4 v[30:33], v172, s[66:67] offset:1024 nt
	global_load_dwordx4 v[34:37], v173, s[66:67] nt
	global_load_dwordx4 v[38:41], v173, s[66:67] offset:1024 nt
	global_load_dwordx4 v[42:45], v174, s[66:67] nt
	global_load_dwordx4 v[46:49], v174, s[66:67] offset:1024 nt
	global_load_dwordx4 v[50:53], v175, s[66:67] nt
	global_load_dwordx4 v[54:57], v175, s[66:67] offset:1024 nt
	s_add_u32 s66, s44, 0x10000
	s_addc_u32 s67, s45, 0
	global_load_dwordx4 v[180:183], v172, s[66:67] nt
	global_load_dwordx4 v[184:187], v172, s[66:67] offset:1024 nt
	global_load_dwordx4 v[188:191], v173, s[66:67] nt
	global_load_dwordx4 v[192:195], v173, s[66:67] offset:1024 nt
	global_load_dwordx4 v[196:199], v174, s[66:67] nt
	global_load_dwordx4 v[200:203], v174, s[66:67] offset:1024 nt
	global_load_dwordx4 v[204:207], v175, s[66:67] nt
	global_load_dwordx4 v[208:211], v175, s[66:67] offset:1024 nt
	s_waitcnt vmcnt(15)
	v_pk_add_f32 v[2:3], v[2:3], v[26:27]
	v_pk_add_f32 v[4:5], v[4:5], v[28:29]
	s_waitcnt vmcnt(14)
	v_pk_add_f32 v[6:7], v[6:7], v[30:31]
	v_pk_add_f32 v[8:9], v[8:9], v[32:33]
	s_waitcnt vmcnt(13)
	v_pk_add_f32 v[2:3], v[2:3], v[34:35]
	v_pk_add_f32 v[4:5], v[4:5], v[36:37]
	s_waitcnt vmcnt(12)
	v_pk_add_f32 v[6:7], v[6:7], v[38:39]
	v_pk_add_f32 v[8:9], v[8:9], v[40:41]
	s_waitcnt vmcnt(11)
	v_pk_add_f32 v[2:3], v[2:3], v[42:43]
	v_pk_add_f32 v[4:5], v[4:5], v[44:45]
	s_waitcnt vmcnt(10)
	v_pk_add_f32 v[6:7], v[6:7], v[46:47]
	v_pk_add_f32 v[8:9], v[8:9], v[48:49]
	s_waitcnt vmcnt(9)
	v_pk_add_f32 v[2:3], v[2:3], v[50:51]
	v_pk_add_f32 v[4:5], v[4:5], v[52:53]
	s_waitcnt vmcnt(8)
	v_pk_add_f32 v[6:7], v[6:7], v[54:55]
	v_pk_add_f32 v[8:9], v[8:9], v[56:57]
	s_add_u32 s66, s44, 0x20000
	s_addc_u32 s67, s45, 0
	global_load_dwordx4 v[26:29], v172, s[66:67] nt
	global_load_dwordx4 v[30:33], v172, s[66:67] offset:1024 nt
	global_load_dwordx4 v[34:37], v173, s[66:67] nt
	global_load_dwordx4 v[38:41], v173, s[66:67] offset:1024 nt
	global_load_dwordx4 v[42:45], v174, s[66:67] nt
	global_load_dwordx4 v[46:49], v174, s[66:67] offset:1024 nt
	global_load_dwordx4 v[50:53], v175, s[66:67] nt
	global_load_dwordx4 v[54:57], v175, s[66:67] offset:1024 nt
	s_waitcnt vmcnt(15)
	v_pk_add_f32 v[2:3], v[2:3], v[180:181]
	v_pk_add_f32 v[4:5], v[4:5], v[182:183]
	s_waitcnt vmcnt(14)
	v_pk_add_f32 v[6:7], v[6:7], v[184:185]
	v_pk_add_f32 v[8:9], v[8:9], v[186:187]
	s_waitcnt vmcnt(13)
	v_pk_add_f32 v[2:3], v[2:3], v[188:189]
	v_pk_add_f32 v[4:5], v[4:5], v[190:191]
	s_waitcnt vmcnt(12)
	v_pk_add_f32 v[6:7], v[6:7], v[192:193]
	v_pk_add_f32 v[8:9], v[8:9], v[194:195]
	s_waitcnt vmcnt(11)
	v_pk_add_f32 v[2:3], v[2:3], v[196:197]
	v_pk_add_f32 v[4:5], v[4:5], v[198:199]
	s_waitcnt vmcnt(10)
	v_pk_add_f32 v[6:7], v[6:7], v[200:201]
	v_pk_add_f32 v[8:9], v[8:9], v[202:203]
	s_waitcnt vmcnt(9)
	v_pk_add_f32 v[2:3], v[2:3], v[204:205]
	v_pk_add_f32 v[4:5], v[4:5], v[206:207]
	s_waitcnt vmcnt(8)
	v_pk_add_f32 v[6:7], v[6:7], v[208:209]
	v_pk_add_f32 v[8:9], v[8:9], v[210:211]
	s_add_u32 s66, s44, 0x30000
	s_addc_u32 s67, s45, 0
	global_load_dwordx4 v[180:183], v172, s[66:67] nt
	global_load_dwordx4 v[184:187], v172, s[66:67] offset:1024 nt
	global_load_dwordx4 v[188:191], v173, s[66:67] nt
	global_load_dwordx4 v[192:195], v173, s[66:67] offset:1024 nt
	global_load_dwordx4 v[196:199], v174, s[66:67] nt
	global_load_dwordx4 v[200:203], v174, s[66:67] offset:1024 nt
	global_load_dwordx4 v[204:207], v175, s[66:67] nt
	global_load_dwordx4 v[208:211], v175, s[66:67] offset:1024 nt
	s_waitcnt vmcnt(15)
	v_pk_add_f32 v[2:3], v[2:3], v[26:27]
	v_pk_add_f32 v[4:5], v[4:5], v[28:29]
	s_waitcnt vmcnt(14)
	v_pk_add_f32 v[6:7], v[6:7], v[30:31]
	v_pk_add_f32 v[8:9], v[8:9], v[32:33]
	s_waitcnt vmcnt(13)
	v_pk_add_f32 v[2:3], v[2:3], v[34:35]
	v_pk_add_f32 v[4:5], v[4:5], v[36:37]
	s_waitcnt vmcnt(12)
	v_pk_add_f32 v[6:7], v[6:7], v[38:39]
	v_pk_add_f32 v[8:9], v[8:9], v[40:41]
	s_waitcnt vmcnt(11)
	v_pk_add_f32 v[2:3], v[2:3], v[42:43]
	v_pk_add_f32 v[4:5], v[4:5], v[44:45]
	s_waitcnt vmcnt(10)
	v_pk_add_f32 v[6:7], v[6:7], v[46:47]
	v_pk_add_f32 v[8:9], v[8:9], v[48:49]
	s_waitcnt vmcnt(9)
	v_pk_add_f32 v[2:3], v[2:3], v[50:51]
	v_pk_add_f32 v[4:5], v[4:5], v[52:53]
	s_waitcnt vmcnt(8)
	v_pk_add_f32 v[6:7], v[6:7], v[54:55]
	v_pk_add_f32 v[8:9], v[8:9], v[56:57]
	s_add_u32 s66, s44, 0x40000
	s_addc_u32 s67, s45, 0
	global_load_dwordx4 v[26:29], v172, s[66:67] nt
	global_load_dwordx4 v[30:33], v172, s[66:67] offset:1024 nt
	global_load_dwordx4 v[34:37], v173, s[66:67] nt
	global_load_dwordx4 v[38:41], v173, s[66:67] offset:1024 nt
	global_load_dwordx4 v[42:45], v174, s[66:67] nt
	global_load_dwordx4 v[46:49], v174, s[66:67] offset:1024 nt
	global_load_dwordx4 v[50:53], v175, s[66:67] nt
	global_load_dwordx4 v[54:57], v175, s[66:67] offset:1024 nt
	s_waitcnt vmcnt(15)
; DI void kmean_item(const float* __restrict__ base, const int* __restrict__ pt, int b, int n, float* __restrict__ outp, char* sm) {
;     ...
;     for (int hf = 0; hf < 2; ++hf) {
;         const int pos0 = n * 256 + hf * 128;
;         const size_t r0 = pt ? (size_t)pt[b * 64 + (pos0 >> 7)] * 128 : (size_t)b * 8192 + pos0;
;         const float* rp = base + (r0 + w) * 1024 + lane * 4;
; #pragma unroll 4
;         for (int rr = 0; rr < 32; ++rr) {
;             a0 += __builtin_nontemporal_load((const f32x4*)(rp + (size_t)rr * 4096));
;             a1 += __builtin_nontemporal_load((const f32x4*)(rp + (size_t)rr * 4096 + 256));
;         }
	v_pk_add_f32 v[2:3], v[2:3], v[180:181]
	v_pk_add_f32 v[4:5], v[4:5], v[182:183]
	s_waitcnt vmcnt(14)
	v_pk_add_f32 v[6:7], v[6:7], v[184:185]
	v_pk_add_f32 v[8:9], v[8:9], v[186:187]
	s_waitcnt vmcnt(13)
	v_pk_add_f32 v[2:3], v[2:3], v[188:189]
	v_pk_add_f32 v[4:5], v[4:5], v[190:191]
	s_waitcnt vmcnt(12)
	v_pk_add_f32 v[6:7], v[6:7], v[192:193]
	v_pk_add_f32 v[8:9], v[8:9], v[194:195]
	s_waitcnt vmcnt(11)
	v_pk_add_f32 v[2:3], v[2:3], v[196:197]
	v_pk_add_f32 v[4:5], v[4:5], v[198:199]
	s_waitcnt vmcnt(10)
	v_pk_add_f32 v[6:7], v[6:7], v[200:201]
	v_pk_add_f32 v[8:9], v[8:9], v[202:203]
	s_waitcnt vmcnt(9)
	v_pk_add_f32 v[2:3], v[2:3], v[204:205]
	v_pk_add_f32 v[4:5], v[4:5], v[206:207]
	s_waitcnt vmcnt(8)
	v_pk_add_f32 v[6:7], v[6:7], v[208:209]
	v_pk_add_f32 v[8:9], v[8:9], v[210:211]
	s_add_u32 s66, s44, 0x50000
	s_addc_u32 s67, s45, 0
	global_load_dwordx4 v[180:183], v172, s[66:67] nt
	global_load_dwordx4 v[184:187], v172, s[66:67] offset:1024 nt
	global_load_dwordx4 v[188:191], v173, s[66:67] nt
	global_load_dwordx4 v[192:195], v173, s[66:67] offset:1024 nt
	global_load_dwordx4 v[196:199], v174, s[66:67] nt
	global_load_dwordx4 v[200:203], v174, s[66:67] offset:1024 nt
	global_load_dwordx4 v[204:207], v175, s[66:67] nt
	global_load_dwordx4 v[208:211], v175, s[66:67] offset:1024 nt
	s_waitcnt vmcnt(15)
	v_pk_add_f32 v[2:3], v[2:3], v[26:27]
	v_pk_add_f32 v[4:5], v[4:5], v[28:29]
	s_waitcnt vmcnt(14)
	v_pk_add_f32 v[6:7], v[6:7], v[30:31]
	v_pk_add_f32 v[8:9], v[8:9], v[32:33]
	s_waitcnt vmcnt(13)
	v_pk_add_f32 v[2:3], v[2:3], v[34:35]
	v_pk_add_f32 v[4:5], v[4:5], v[36:37]
	s_waitcnt vmcnt(12)
	v_pk_add_f32 v[6:7], v[6:7], v[38:39]
	v_pk_add_f32 v[8:9], v[8:9], v[40:41]
	s_waitcnt vmcnt(11)
	v_pk_add_f32 v[2:3], v[2:3], v[42:43]
	v_pk_add_f32 v[4:5], v[4:5], v[44:45]
	s_waitcnt vmcnt(10)
	v_pk_add_f32 v[6:7], v[6:7], v[46:47]
	v_pk_add_f32 v[8:9], v[8:9], v[48:49]
	s_waitcnt vmcnt(9)
	v_pk_add_f32 v[2:3], v[2:3], v[50:51]
	v_pk_add_f32 v[4:5], v[4:5], v[52:53]
	s_waitcnt vmcnt(8)
	v_pk_add_f32 v[6:7], v[6:7], v[54:55]
	v_pk_add_f32 v[8:9], v[8:9], v[56:57]
	s_add_u32 s66, s44, 0x60000
	s_addc_u32 s67, s45, 0
	global_load_dwordx4 v[26:29], v172, s[66:67] nt
	global_load_dwordx4 v[30:33], v172, s[66:67] offset:1024 nt
	global_load_dwordx4 v[34:37], v173, s[66:67] nt
	global_load_dwordx4 v[38:41], v173, s[66:67] offset:1024 nt
	global_load_dwordx4 v[42:45], v174, s[66:67] nt
	global_load_dwordx4 v[46:49], v174, s[66:67] offset:1024 nt
	global_load_dwordx4 v[50:53], v175, s[66:67] nt
	global_load_dwordx4 v[54:57], v175, s[66:67] offset:1024 nt
	s_waitcnt vmcnt(15)
	v_pk_add_f32 v[2:3], v[2:3], v[180:181]
	v_pk_add_f32 v[4:5], v[4:5], v[182:183]
	s_waitcnt vmcnt(14)
	v_pk_add_f32 v[6:7], v[6:7], v[184:185]
	v_pk_add_f32 v[8:9], v[8:9], v[186:187]
	s_waitcnt vmcnt(13)
	v_pk_add_f32 v[2:3], v[2:3], v[188:189]
	v_pk_add_f32 v[4:5], v[4:5], v[190:191]
	s_waitcnt vmcnt(12)
	v_pk_add_f32 v[6:7], v[6:7], v[192:193]
	v_pk_add_f32 v[8:9], v[8:9], v[194:195]
	s_waitcnt vmcnt(11)
	v_pk_add_f32 v[2:3], v[2:3], v[196:197]
	v_pk_add_f32 v[4:5], v[4:5], v[198:199]
	s_waitcnt vmcnt(10)
	v_pk_add_f32 v[6:7], v[6:7], v[200:201]
	v_pk_add_f32 v[8:9], v[8:9], v[202:203]
	s_waitcnt vmcnt(9)
	v_pk_add_f32 v[2:3], v[2:3], v[204:205]
	v_pk_add_f32 v[4:5], v[4:5], v[206:207]
	s_waitcnt vmcnt(8)
	v_pk_add_f32 v[6:7], v[6:7], v[208:209]
	v_pk_add_f32 v[8:9], v[8:9], v[210:211]
	s_add_u32 s66, s44, 0x70000
	s_addc_u32 s67, s45, 0
	global_load_dwordx4 v[180:183], v172, s[66:67] nt
	global_load_dwordx4 v[184:187], v172, s[66:67] offset:1024 nt
	global_load_dwordx4 v[188:191], v173, s[66:67] nt
	global_load_dwordx4 v[192:195], v173, s[66:67] offset:1024 nt
	global_load_dwordx4 v[196:199], v174, s[66:67] nt
	global_load_dwordx4 v[200:203], v174, s[66:67] offset:1024 nt
	global_load_dwordx4 v[204:207], v175, s[66:67] nt
	global_load_dwordx4 v[208:211], v175, s[66:67] offset:1024 nt
	s_waitcnt vmcnt(15)
	v_pk_add_f32 v[2:3], v[2:3], v[26:27]
	v_pk_add_f32 v[4:5], v[4:5], v[28:29]
	s_waitcnt vmcnt(14)
	v_pk_add_f32 v[6:7], v[6:7], v[30:31]
	v_pk_add_f32 v[8:9], v[8:9], v[32:33]
	s_waitcnt vmcnt(13)
	v_pk_add_f32 v[2:3], v[2:3], v[34:35]
	v_pk_add_f32 v[4:5], v[4:5], v[36:37]
	s_waitcnt vmcnt(12)
	v_pk_add_f32 v[6:7], v[6:7], v[38:39]
	v_pk_add_f32 v[8:9], v[8:9], v[40:41]
	s_waitcnt vmcnt(11)
	v_pk_add_f32 v[2:3], v[2:3], v[42:43]
	v_pk_add_f32 v[4:5], v[4:5], v[44:45]
	s_waitcnt vmcnt(10)
	v_pk_add_f32 v[6:7], v[6:7], v[46:47]
	v_pk_add_f32 v[8:9], v[8:9], v[48:49]
	s_waitcnt vmcnt(9)
	v_pk_add_f32 v[2:3], v[2:3], v[50:51]
	v_pk_add_f32 v[4:5], v[4:5], v[52:53]
	s_waitcnt vmcnt(8)
	v_pk_add_f32 v[6:7], v[6:7], v[54:55]
	v_pk_add_f32 v[8:9], v[8:9], v[56:57]
	s_mov_b64 s[66:67], s[44:45]
	global_load_dwordx4 v[26:29], v176, s[66:67] nt
	global_load_dwordx4 v[30:33], v176, s[66:67] offset:1024 nt
	global_load_dwordx4 v[34:37], v177, s[66:67] nt
	global_load_dwordx4 v[38:41], v177, s[66:67] offset:1024 nt
	global_load_dwordx4 v[42:45], v178, s[66:67] nt
	global_load_dwordx4 v[46:49], v178, s[66:67] offset:1024 nt
	global_load_dwordx4 v[50:53], v179, s[66:67] nt
	global_load_dwordx4 v[54:57], v179, s[66:67] offset:1024 nt
	s_waitcnt vmcnt(15)
	v_pk_add_f32 v[2:3], v[2:3], v[180:181]
	v_pk_add_f32 v[4:5], v[4:5], v[182:183]
	s_waitcnt vmcnt(14)
	v_pk_add_f32 v[6:7], v[6:7], v[184:185]
	v_pk_add_f32 v[8:9], v[8:9], v[186:187]
	s_waitcnt vmcnt(13)
	v_pk_add_f32 v[2:3], v[2:3], v[188:189]
	v_pk_add_f32 v[4:5], v[4:5], v[190:191]
	s_waitcnt vmcnt(12)
	v_pk_add_f32 v[6:7], v[6:7], v[192:193]
	v_pk_add_f32 v[8:9], v[8:9], v[194:195]
	s_waitcnt vmcnt(11)
; DI void kmean_item(const float* __restrict__ base, const int* __restrict__ pt, int b, int n, float* __restrict__ outp, char* sm) {
;     ...
;     for (int hf = 0; hf < 2; ++hf) {
;         const int pos0 = n * 256 + hf * 128;
;         const size_t r0 = pt ? (size_t)pt[b * 64 + (pos0 >> 7)] * 128 : (size_t)b * 8192 + pos0;
;         const float* rp = base + (r0 + w) * 1024 + lane * 4;
; #pragma unroll 4
;         for (int rr = 0; rr < 32; ++rr) {
;             a0 += __builtin_nontemporal_load((const f32x4*)(rp + (size_t)rr * 4096));
;             a1 += __builtin_nontemporal_load((const f32x4*)(rp + (size_t)rr * 4096 + 256));
;         }
	v_pk_add_f32 v[2:3], v[2:3], v[196:197]
	v_pk_add_f32 v[4:5], v[4:5], v[198:199]
	s_waitcnt vmcnt(10)
	v_pk_add_f32 v[6:7], v[6:7], v[200:201]
	v_pk_add_f32 v[8:9], v[8:9], v[202:203]
	s_waitcnt vmcnt(9)
	v_pk_add_f32 v[2:3], v[2:3], v[204:205]
	v_pk_add_f32 v[4:5], v[4:5], v[206:207]
	s_waitcnt vmcnt(8)
	v_pk_add_f32 v[6:7], v[6:7], v[208:209]
	v_pk_add_f32 v[8:9], v[8:9], v[210:211]
	s_add_u32 s66, s44, 0x10000
	s_addc_u32 s67, s45, 0
	global_load_dwordx4 v[180:183], v176, s[66:67] nt
	global_load_dwordx4 v[184:187], v176, s[66:67] offset:1024 nt
	global_load_dwordx4 v[188:191], v177, s[66:67] nt
	global_load_dwordx4 v[192:195], v177, s[66:67] offset:1024 nt
	global_load_dwordx4 v[196:199], v178, s[66:67] nt
	global_load_dwordx4 v[200:203], v178, s[66:67] offset:1024 nt
	global_load_dwordx4 v[204:207], v179, s[66:67] nt
	global_load_dwordx4 v[208:211], v179, s[66:67] offset:1024 nt
	s_waitcnt vmcnt(15)
	v_pk_add_f32 v[2:3], v[2:3], v[26:27]
	v_pk_add_f32 v[4:5], v[4:5], v[28:29]
	s_waitcnt vmcnt(14)
	v_pk_add_f32 v[6:7], v[6:7], v[30:31]
	v_pk_add_f32 v[8:9], v[8:9], v[32:33]
	s_waitcnt vmcnt(13)
	v_pk_add_f32 v[2:3], v[2:3], v[34:35]
	v_pk_add_f32 v[4:5], v[4:5], v[36:37]
	s_waitcnt vmcnt(12)
	v_pk_add_f32 v[6:7], v[6:7], v[38:39]
	v_pk_add_f32 v[8:9], v[8:9], v[40:41]
	s_waitcnt vmcnt(11)
	v_pk_add_f32 v[2:3], v[2:3], v[42:43]
	v_pk_add_f32 v[4:5], v[4:5], v[44:45]
	s_waitcnt vmcnt(10)
	v_pk_add_f32 v[6:7], v[6:7], v[46:47]
	v_pk_add_f32 v[8:9], v[8:9], v[48:49]
	s_waitcnt vmcnt(9)
	v_pk_add_f32 v[2:3], v[2:3], v[50:51]
	v_pk_add_f32 v[4:5], v[4:5], v[52:53]
	s_waitcnt vmcnt(8)
	v_pk_add_f32 v[6:7], v[6:7], v[54:55]
	v_pk_add_f32 v[8:9], v[8:9], v[56:57]
	s_add_u32 s66, s44, 0x20000
	s_addc_u32 s67, s45, 0
	global_load_dwordx4 v[26:29], v176, s[66:67] nt
	global_load_dwordx4 v[30:33], v176, s[66:67] offset:1024 nt
	global_load_dwordx4 v[34:37], v177, s[66:67] nt
	global_load_dwordx4 v[38:41], v177, s[66:67] offset:1024 nt
	global_load_dwordx4 v[42:45], v178, s[66:67] nt
	global_load_dwordx4 v[46:49], v178, s[66:67] offset:1024 nt
	global_load_dwordx4 v[50:53], v179, s[66:67] nt
	global_load_dwordx4 v[54:57], v179, s[66:67] offset:1024 nt
	s_waitcnt vmcnt(15)
	v_pk_add_f32 v[2:3], v[2:3], v[180:181]
	v_pk_add_f32 v[4:5], v[4:5], v[182:183]
	s_waitcnt vmcnt(14)
	v_pk_add_f32 v[6:7], v[6:7], v[184:185]
	v_pk_add_f32 v[8:9], v[8:9], v[186:187]
	s_waitcnt vmcnt(13)
	v_pk_add_f32 v[2:3], v[2:3], v[188:189]
	v_pk_add_f32 v[4:5], v[4:5], v[190:191]
	s_waitcnt vmcnt(12)
	v_pk_add_f32 v[6:7], v[6:7], v[192:193]
	v_pk_add_f32 v[8:9], v[8:9], v[194:195]
	s_waitcnt vmcnt(11)
	v_pk_add_f32 v[2:3], v[2:3], v[196:197]
	v_pk_add_f32 v[4:5], v[4:5], v[198:199]
	s_waitcnt vmcnt(10)
	v_pk_add_f32 v[6:7], v[6:7], v[200:201]
	v_pk_add_f32 v[8:9], v[8:9], v[202:203]
	s_waitcnt vmcnt(9)
	v_pk_add_f32 v[2:3], v[2:3], v[204:205]
	v_pk_add_f32 v[4:5], v[4:5], v[206:207]
	s_waitcnt vmcnt(8)
	v_pk_add_f32 v[6:7], v[6:7], v[208:209]
	v_pk_add_f32 v[8:9], v[8:9], v[210:211]
	s_add_u32 s66, s44, 0x30000
	s_addc_u32 s67, s45, 0
	global_load_dwordx4 v[180:183], v176, s[66:67] nt
	global_load_dwordx4 v[184:187], v176, s[66:67] offset:1024 nt
	global_load_dwordx4 v[188:191], v177, s[66:67] nt
	global_load_dwordx4 v[192:195], v177, s[66:67] offset:1024 nt
	global_load_dwordx4 v[196:199], v178, s[66:67] nt
	global_load_dwordx4 v[200:203], v178, s[66:67] offset:1024 nt
	global_load_dwordx4 v[204:207], v179, s[66:67] nt
	global_load_dwordx4 v[208:211], v179, s[66:67] offset:1024 nt
	s_waitcnt vmcnt(15)
	v_pk_add_f32 v[2:3], v[2:3], v[26:27]
	v_pk_add_f32 v[4:5], v[4:5], v[28:29]
	s_waitcnt vmcnt(14)
	v_pk_add_f32 v[6:7], v[6:7], v[30:31]
	v_pk_add_f32 v[8:9], v[8:9], v[32:33]
	s_waitcnt vmcnt(13)
	v_pk_add_f32 v[2:3], v[2:3], v[34:35]
	v_pk_add_f32 v[4:5], v[4:5], v[36:37]
	s_waitcnt vmcnt(12)
	v_pk_add_f32 v[6:7], v[6:7], v[38:39]
	v_pk_add_f32 v[8:9], v[8:9], v[40:41]
	s_waitcnt vmcnt(11)
	v_pk_add_f32 v[2:3], v[2:3], v[42:43]
	v_pk_add_f32 v[4:5], v[4:5], v[44:45]
	s_waitcnt vmcnt(10)
	v_pk_add_f32 v[6:7], v[6:7], v[46:47]
	v_pk_add_f32 v[8:9], v[8:9], v[48:49]
	s_waitcnt vmcnt(9)
	v_pk_add_f32 v[2:3], v[2:3], v[50:51]
	v_pk_add_f32 v[4:5], v[4:5], v[52:53]
	s_waitcnt vmcnt(8)
	v_pk_add_f32 v[6:7], v[6:7], v[54:55]
	v_pk_add_f32 v[8:9], v[8:9], v[56:57]
	s_add_u32 s66, s44, 0x40000
	s_addc_u32 s67, s45, 0
	global_load_dwordx4 v[26:29], v176, s[66:67] nt
	global_load_dwordx4 v[30:33], v176, s[66:67] offset:1024 nt
	global_load_dwordx4 v[34:37], v177, s[66:67] nt
	global_load_dwordx4 v[38:41], v177, s[66:67] offset:1024 nt
	global_load_dwordx4 v[42:45], v178, s[66:67] nt
	global_load_dwordx4 v[46:49], v178, s[66:67] offset:1024 nt
	global_load_dwordx4 v[50:53], v179, s[66:67] nt
	global_load_dwordx4 v[54:57], v179, s[66:67] offset:1024 nt
	s_waitcnt vmcnt(15)
	v_pk_add_f32 v[2:3], v[2:3], v[180:181]
	v_pk_add_f32 v[4:5], v[4:5], v[182:183]
	s_waitcnt vmcnt(14)
	v_pk_add_f32 v[6:7], v[6:7], v[184:185]
	v_pk_add_f32 v[8:9], v[8:9], v[186:187]
	s_waitcnt vmcnt(13)
	v_pk_add_f32 v[2:3], v[2:3], v[188:189]
	v_pk_add_f32 v[4:5], v[4:5], v[190:191]
	s_waitcnt vmcnt(12)
	v_pk_add_f32 v[6:7], v[6:7], v[192:193]
	v_pk_add_f32 v[8:9], v[8:9], v[194:195]
	s_waitcnt vmcnt(11)
	v_pk_add_f32 v[2:3], v[2:3], v[196:197]
	v_pk_add_f32 v[4:5], v[4:5], v[198:199]
	s_waitcnt vmcnt(10)
	v_pk_add_f32 v[6:7], v[6:7], v[200:201]
	v_pk_add_f32 v[8:9], v[8:9], v[202:203]
	s_waitcnt vmcnt(9)
	v_pk_add_f32 v[2:3], v[2:3], v[204:205]
	v_pk_add_f32 v[4:5], v[4:5], v[206:207]
	s_waitcnt vmcnt(8)
; DI void kmean_item(const float* __restrict__ base, const int* __restrict__ pt, int b, int n, float* __restrict__ outp, char* sm) {
;     ...
; #pragma unroll 4
;         for (int rr = 0; rr < 32; ++rr) {
;             a0 += __builtin_nontemporal_load((const f32x4*)(rp + (size_t)rr * 4096));
;             a1 += __builtin_nontemporal_load((const f32x4*)(rp + (size_t)rr * 4096 + 256));
;         }
;     }
;     *(f32x4*)(scr + w * 512 + lane * 4) = a0;
;     *(f32x4*)(scr + w * 512 + 256 + lane * 4) = a1;
;     __syncthreads();
; #pragma unroll
;     for (int j = 0; j < 2; ++j) {
;         const int col = t + 256 * j;
;         outp[col] = (scr[col] + scr[512 + col] + scr[1024 + col] + scr[1536 + col]) * (1.f / 256.f);
;     }
;     __syncthreads();
	v_pk_add_f32 v[6:7], v[6:7], v[208:209]
	v_pk_add_f32 v[8:9], v[8:9], v[210:211]
	s_add_u32 s66, s44, 0x50000
	s_addc_u32 s67, s45, 0
	global_load_dwordx4 v[180:183], v176, s[66:67] nt
	global_load_dwordx4 v[184:187], v176, s[66:67] offset:1024 nt
	global_load_dwordx4 v[188:191], v177, s[66:67] nt
	global_load_dwordx4 v[192:195], v177, s[66:67] offset:1024 nt
	global_load_dwordx4 v[196:199], v178, s[66:67] nt
	global_load_dwordx4 v[200:203], v178, s[66:67] offset:1024 nt
	global_load_dwordx4 v[204:207], v179, s[66:67] nt
	global_load_dwordx4 v[208:211], v179, s[66:67] offset:1024 nt
	s_waitcnt vmcnt(15)
	v_pk_add_f32 v[2:3], v[2:3], v[26:27]
	v_pk_add_f32 v[4:5], v[4:5], v[28:29]
	s_waitcnt vmcnt(14)
	v_pk_add_f32 v[6:7], v[6:7], v[30:31]
	v_pk_add_f32 v[8:9], v[8:9], v[32:33]
	s_waitcnt vmcnt(13)
	v_pk_add_f32 v[2:3], v[2:3], v[34:35]
	v_pk_add_f32 v[4:5], v[4:5], v[36:37]
	s_waitcnt vmcnt(12)
	v_pk_add_f32 v[6:7], v[6:7], v[38:39]
	v_pk_add_f32 v[8:9], v[8:9], v[40:41]
	s_waitcnt vmcnt(11)
	v_pk_add_f32 v[2:3], v[2:3], v[42:43]
	v_pk_add_f32 v[4:5], v[4:5], v[44:45]
	s_waitcnt vmcnt(10)
	v_pk_add_f32 v[6:7], v[6:7], v[46:47]
	v_pk_add_f32 v[8:9], v[8:9], v[48:49]
	s_waitcnt vmcnt(9)
	v_pk_add_f32 v[2:3], v[2:3], v[50:51]
	v_pk_add_f32 v[4:5], v[4:5], v[52:53]
	s_waitcnt vmcnt(8)
	v_pk_add_f32 v[6:7], v[6:7], v[54:55]
	v_pk_add_f32 v[8:9], v[8:9], v[56:57]
	s_add_u32 s66, s44, 0x60000
	s_addc_u32 s67, s45, 0
	global_load_dwordx4 v[26:29], v176, s[66:67] nt
	global_load_dwordx4 v[30:33], v176, s[66:67] offset:1024 nt
	global_load_dwordx4 v[34:37], v177, s[66:67] nt
	global_load_dwordx4 v[38:41], v177, s[66:67] offset:1024 nt
	global_load_dwordx4 v[42:45], v178, s[66:67] nt
	global_load_dwordx4 v[46:49], v178, s[66:67] offset:1024 nt
	global_load_dwordx4 v[50:53], v179, s[66:67] nt
	global_load_dwordx4 v[54:57], v179, s[66:67] offset:1024 nt
	s_waitcnt vmcnt(15)
	v_pk_add_f32 v[2:3], v[2:3], v[180:181]
	v_pk_add_f32 v[4:5], v[4:5], v[182:183]
	s_waitcnt vmcnt(14)
	v_pk_add_f32 v[6:7], v[6:7], v[184:185]
	v_pk_add_f32 v[8:9], v[8:9], v[186:187]
	s_waitcnt vmcnt(13)
	v_pk_add_f32 v[2:3], v[2:3], v[188:189]
	v_pk_add_f32 v[4:5], v[4:5], v[190:191]
	s_waitcnt vmcnt(12)
	v_pk_add_f32 v[6:7], v[6:7], v[192:193]
	v_pk_add_f32 v[8:9], v[8:9], v[194:195]
	s_waitcnt vmcnt(11)
	v_pk_add_f32 v[2:3], v[2:3], v[196:197]
	v_pk_add_f32 v[4:5], v[4:5], v[198:199]
	s_waitcnt vmcnt(10)
	v_pk_add_f32 v[6:7], v[6:7], v[200:201]
	v_pk_add_f32 v[8:9], v[8:9], v[202:203]
	s_waitcnt vmcnt(9)
	v_pk_add_f32 v[2:3], v[2:3], v[204:205]
	v_pk_add_f32 v[4:5], v[4:5], v[206:207]
	s_waitcnt vmcnt(8)
	v_pk_add_f32 v[6:7], v[6:7], v[208:209]
	v_pk_add_f32 v[8:9], v[8:9], v[210:211]
	s_add_u32 s66, s44, 0x70000
	s_addc_u32 s67, s45, 0
	global_load_dwordx4 v[180:183], v176, s[66:67] nt
	global_load_dwordx4 v[184:187], v176, s[66:67] offset:1024 nt
	global_load_dwordx4 v[188:191], v177, s[66:67] nt
	global_load_dwordx4 v[192:195], v177, s[66:67] offset:1024 nt
	global_load_dwordx4 v[196:199], v178, s[66:67] nt
	global_load_dwordx4 v[200:203], v178, s[66:67] offset:1024 nt
	global_load_dwordx4 v[204:207], v179, s[66:67] nt
	global_load_dwordx4 v[208:211], v179, s[66:67] offset:1024 nt
	s_waitcnt vmcnt(15)
	v_pk_add_f32 v[2:3], v[2:3], v[26:27]
	v_pk_add_f32 v[4:5], v[4:5], v[28:29]
	s_waitcnt vmcnt(14)
	v_pk_add_f32 v[6:7], v[6:7], v[30:31]
	v_pk_add_f32 v[8:9], v[8:9], v[32:33]
	s_waitcnt vmcnt(13)
	v_pk_add_f32 v[2:3], v[2:3], v[34:35]
	v_pk_add_f32 v[4:5], v[4:5], v[36:37]
	s_waitcnt vmcnt(12)
	v_pk_add_f32 v[6:7], v[6:7], v[38:39]
	v_pk_add_f32 v[8:9], v[8:9], v[40:41]
	s_waitcnt vmcnt(11)
	v_pk_add_f32 v[2:3], v[2:3], v[42:43]
	v_pk_add_f32 v[4:5], v[4:5], v[44:45]
	s_waitcnt vmcnt(10)
	v_pk_add_f32 v[6:7], v[6:7], v[46:47]
	v_pk_add_f32 v[8:9], v[8:9], v[48:49]
	s_waitcnt vmcnt(9)
	v_pk_add_f32 v[2:3], v[2:3], v[50:51]
	v_pk_add_f32 v[4:5], v[4:5], v[52:53]
	s_waitcnt vmcnt(8)
	v_pk_add_f32 v[6:7], v[6:7], v[54:55]
	v_pk_add_f32 v[8:9], v[8:9], v[56:57]
	s_waitcnt vmcnt(7)
	v_pk_add_f32 v[2:3], v[2:3], v[180:181]
	v_pk_add_f32 v[4:5], v[4:5], v[182:183]
	s_waitcnt vmcnt(6)
	v_pk_add_f32 v[6:7], v[6:7], v[184:185]
	v_pk_add_f32 v[8:9], v[8:9], v[186:187]
	s_waitcnt vmcnt(5)
	v_pk_add_f32 v[2:3], v[2:3], v[188:189]
	v_pk_add_f32 v[4:5], v[4:5], v[190:191]
	s_waitcnt vmcnt(4)
	v_pk_add_f32 v[6:7], v[6:7], v[192:193]
	v_pk_add_f32 v[8:9], v[8:9], v[194:195]
	s_waitcnt vmcnt(3)
	v_pk_add_f32 v[2:3], v[2:3], v[196:197]
	v_pk_add_f32 v[4:5], v[4:5], v[198:199]
	s_waitcnt vmcnt(2)
	v_pk_add_f32 v[6:7], v[6:7], v[200:201]
	v_pk_add_f32 v[8:9], v[8:9], v[202:203]
	s_waitcnt vmcnt(1)
	v_pk_add_f32 v[2:3], v[2:3], v[204:205]
	v_pk_add_f32 v[4:5], v[4:5], v[206:207]
	s_waitcnt vmcnt(0)
	v_pk_add_f32 v[6:7], v[6:7], v[208:209]
	v_pk_add_f32 v[8:9], v[8:9], v[210:211]
	v_lshlrev_b32_e32 v11, 11, v12
	v_add_u32_e32 v11, v11, v18
	v_add_u32_e32 v11, 0x8000, v11
	ds_write_b128 v11, v[2:5]
	ds_write_b128 v11, v[6:9] offset:1024
	v_lshlrev_b32_e32 v13, 2, v0
	v_add_u32_e32 v14, 0x8000, v13
	s_lshl_b32 s64, s59, 11
	s_add_u32 s64, s62, s64
	s_addc_u32 s65, s63, 0
	s_add_u32 s64, s64, 0xbb6000
	s_addc_u32 s65, s65, 0
	s_waitcnt lgkmcnt(0)
	s_barrier
	ds_read2st64_b32 v[2:3], v14 offset1:4
	ds_read2st64_b32 v[4:5], v14 offset0:8 offset1:12
	ds_read2st64_b32 v[6:7], v14 offset0:16 offset1:20
	ds_read2st64_b32 v[8:9], v14 offset0:24 offset1:28
	s_waitcnt lgkmcnt(2)
	v_add_f32_e32 v11, v2, v4
	s_waitcnt lgkmcnt(1)
	v_add_f32_e32 v11, v11, v6
	s_waitcnt lgkmcnt(0)
	v_add_f32_e32 v11, v11, v8
	v_mul_f32_e32 v11, 0x3b800000, v11
	global_store_dword v13, v11, s[64:65]
	v_add_f32_e32 v11, v3, v5
	v_add_f32_e32 v11, v11, v7
	v_add_f32_e32 v11, v11, v9
	v_mul_f32_e32 v11, 0x3b800000, v11
	global_store_dword v13, v11, s[64:65] offset:1024
	s_barrier
	s_branch .Lkm3_ret

; DI void nsa_item(const Params& p, char* sm, bool dec, int b, int kvh, int q32) {
;     ...
;             for (int k = 1; k <= cur - 2; ++k) {
;                 const unsigned long long x = ((unsigned long long)__float_as_uint(imp[qc * IMPLD + k]) << 32) | (unsigned)(255 - k);
; #pragma unroll
;                 for (int jj = 0; jj < 16; ++jj) cnt[jj] += x > v[jj] ? 1 : 0;
;             }
.LBB0_1323:
	ds_read2_b32 v[174:175], v124 offset1:1
	s_sub_i32 s20, 0xff, s0
	v_mov_b32_e32 v176, s20
	s_sub_i32 s21, 0xff, s3
	v_mov_b32_e32 v178, s21
	s_waitcnt lgkmcnt(0)
	v_mov_b32_e32 v177, v175
	v_mov_b32_e32 v179, v174
	s_add_i32 s3, s3, 2
	s_add_i32 s0, s0, 2
	s_add_i32 s17, s17, -2
	v_add_u32_e32 v124, 8, v124
	s_cmp_lg_u32 s17, 0
	v_cmp_gt_u64_e64 s[22:23], v[176:177], v[50:51]
	v_cmp_gt_u64_e64 s[24:25], v[178:179], v[48:49]
	v_cmp_gt_u64_e64 s[28:29], v[176:177], v[54:55]
	v_addc_co_u32_e64 v154, vcc, 0, v154, s[22:23]
	v_cmp_gt_u64_e64 s[22:23], v[178:179], v[52:53]
	v_addc_co_u32_e64 v151, vcc, 0, v151, s[24:25]
	v_cmp_gt_u64_e64 s[24:25], v[176:177], v[58:59]
	v_addc_co_u32_e64 v157, vcc, 0, v157, s[28:29]
	v_cmp_gt_u64_e64 s[28:29], v[178:179], v[56:57]
	v_addc_co_u32_e64 v153, vcc, 0, v153, s[22:23]
	v_cmp_gt_u64_e64 s[22:23], v[176:177], v[62:63]
	v_addc_co_u32_e64 v152, vcc, 0, v152, s[24:25]
	v_cmp_gt_u64_e64 s[24:25], v[178:179], v[60:61]
	v_addc_co_u32_e64 v150, vcc, 0, v150, s[28:29]
	v_cmp_gt_u64_e64 s[28:29], v[176:177], v[64:65]
	v_addc_co_u32_e64 v149, vcc, 0, v149, s[22:23]
	v_cmp_gt_u64_e64 s[22:23], v[178:179], v[36:37]
	v_addc_co_u32_e64 v148, vcc, 0, v148, s[24:25]
	v_cmp_gt_u64_e64 s[24:25], v[176:177], v[68:69]
	v_addc_co_u32_e64 v147, vcc, 0, v147, s[28:29]
	v_cmp_gt_u64_e64 s[28:29], v[178:179], v[66:67]
	v_addc_co_u32_e64 v146, vcc, 0, v146, s[22:23]
	v_cmp_gt_u64_e64 s[22:23], v[176:177], v[70:71]
	v_addc_co_u32_e64 v145, vcc, 0, v145, s[24:25]
	v_cmp_gt_u64_e64 s[24:25], v[178:179], v[38:39]
	v_addc_co_u32_e64 v144, vcc, 0, v144, s[28:29]
	v_cmp_gt_u64_e64 s[28:29], v[176:177], v[74:75]
	v_addc_co_u32_e64 v143, vcc, 0, v143, s[22:23]
	v_cmp_gt_u64_e64 s[22:23], v[178:179], v[72:73]
	v_addc_co_u32_e64 v142, vcc, 0, v142, s[24:25]
	v_cmp_gt_u64_e64 s[24:25], v[176:177], v[76:77]
	v_addc_co_u32_e64 v141, vcc, 0, v141, s[28:29]
	v_cmp_gt_u64_e64 s[28:29], v[178:179], v[40:41]
	v_addc_co_u32_e64 v140, vcc, 0, v140, s[22:23]
	v_cmp_gt_u64_e64 s[22:23], v[176:177], v[80:81]
	v_addc_co_u32_e64 v139, vcc, 0, v139, s[24:25]
	v_cmp_gt_u64_e64 s[24:25], v[178:179], v[78:79]
	v_addc_co_u32_e64 v138, vcc, 0, v138, s[28:29]
	v_cmp_gt_u64_e64 s[28:29], v[176:177], v[82:83]
	v_addc_co_u32_e64 v137, vcc, 0, v137, s[22:23]
	v_cmp_gt_u64_e64 s[22:23], v[178:179], v[42:43]
	v_addc_co_u32_e64 v136, vcc, 0, v136, s[24:25]
	v_cmp_gt_u64_e64 s[24:25], v[176:177], v[110:111]
	v_addc_co_u32_e64 v135, vcc, 0, v135, s[28:29]
	v_cmp_gt_u64_e64 s[28:29], v[178:179], v[84:85]
	v_addc_co_u32_e64 v134, vcc, 0, v134, s[22:23]
	v_cmp_gt_u64_e64 s[22:23], v[176:177], v[112:113]
	v_addc_co_u32_e64 v133, vcc, 0, v133, s[24:25]
	v_cmp_gt_u64_e64 s[24:25], v[178:179], v[44:45]
	v_addc_co_u32_e64 v132, vcc, 0, v132, s[28:29]
	v_cmp_gt_u64_e64 s[28:29], v[176:177], v[116:117]
	v_addc_co_u32_e64 v131, vcc, 0, v131, s[22:23]
	v_cmp_gt_u64_e64 s[22:23], v[178:179], v[114:115]
	v_addc_co_u32_e64 v130, vcc, 0, v130, s[24:25]
	v_cmp_gt_u64_e64 s[24:25], v[176:177], v[118:119]
	v_addc_co_u32_e64 v129, vcc, 0, v129, s[28:29]
	v_cmp_gt_u64_e64 s[28:29], v[178:179], v[46:47]
	v_addc_co_u32_e64 v128, vcc, 0, v128, s[22:23]
	v_cmp_gt_u64_e64 s[22:23], v[176:177], v[120:121]
	v_addc_co_u32_e64 v127, vcc, 0, v127, s[24:25]
	v_cmp_gt_u64_e64 s[24:25], v[178:179], v[6:7]
	v_addc_co_u32_e64 v126, vcc, 0, v126, s[28:29]
	v_addc_co_u32_e64 v125, vcc, 0, v125, s[22:23]
	v_addc_co_u32_e64 v123, vcc, 0, v123, s[24:25]
	s_cbranch_scc1 .LBB0_1323
	v_add_u32_e32 v36, v123, v125
	v_add_u32_e32 v37, v126, v127
	v_add_u32_e32 v38, v128, v129
	v_add_u32_e32 v39, v130, v131
	v_add_u32_e32 v40, v132, v133
	v_add_u32_e32 v41, v134, v135
	v_add_u32_e32 v42, v136, v137
	v_add_u32_e32 v43, v138, v139
	v_add_u32_e32 v44, v140, v141
	v_add_u32_e32 v45, v142, v143
	v_add_u32_e32 v46, v144, v145
	v_add_u32_e32 v47, v146, v147
	v_add_u32_e32 v48, v148, v149
	v_add_u32_e32 v49, v150, v152
	v_add_u32_e32 v50, v153, v157
	s_cmp_eq_u32 s1, s2
	v_add_u32_e32 v51, v151, v154
	s_cbranch_scc1 .LBB0_1327
	s_or_b32 s1, s1, 1
	s_lshl_b32 s0, s1, 2
	s_add_i32 s0, s0, 0
	s_add_i32 s0, s0, 0xb700
	v_add_u32_e32 v52, s0, v122
	s_sub_i32 s0, 0, s16
	s_not_b32 s1, s1

; __global__ void __launch_bounds__(NTHREADS, 2) mega_kernel(Params p) {
;     extern __shared__ __attribute__((aligned(16))) char sm[];
	.amdhsa_kernel _Z11mega_kernel6Params
		.amdhsa_group_segment_fixed_size 0
		.amdhsa_private_segment_fixed_size 0
		.amdhsa_kernarg_size 432
		.amdhsa_user_sgpr_count 2
		.amdhsa_user_sgpr_dispatch_ptr 0
		.amdhsa_user_sgpr_queue_ptr 0
		.amdhsa_user_sgpr_kernarg_segment_ptr 1
		.amdhsa_user_sgpr_dispatch_id 0
		.amdhsa_user_sgpr_kernarg_preload_length 0
		.amdhsa_user_sgpr_kernarg_preload_offset 0
		.amdhsa_user_sgpr_private_segment_size 0
		.amdhsa_uses_dynamic_stack 0
		.amdhsa_enable_private_segment 0
		.amdhsa_system_sgpr_workgroup_id_x 1
		.amdhsa_system_sgpr_workgroup_id_y 0
		.amdhsa_system_sgpr_workgroup_id_z 0
		.amdhsa_system_sgpr_workgroup_info 0
		.amdhsa_system_vgpr_workitem_id 0
		.amdhsa_next_free_vgpr 256
		.amdhsa_next_free_sgpr 102
		.amdhsa_accum_offset 256
		.amdhsa_reserve_vcc 1
		.amdhsa_float_round_mode_32 0
		.amdhsa_float_round_mode_16_64 0
		.amdhsa_float_denorm_mode_32 3
		.amdhsa_float_denorm_mode_16_64 3
		.amdhsa_dx10_clamp 1
		.amdhsa_ieee_mode 1
		.amdhsa_fp16_overflow 0
		.amdhsa_tg_split 0
		.amdhsa_exception_fp_ieee_invalid_op 0
		.amdhsa_exception_fp_denorm_src 0
		.amdhsa_exception_fp_ieee_div_zero 0
		.amdhsa_exception_fp_ieee_overflow 0
		.amdhsa_exception_fp_ieee_underflow 0
		.amdhsa_exception_fp_ieee_inexact 0
		.amdhsa_exception_int_div_zero 0
	.end_amdhsa_kernel

; __global__ void __launch_bounds__(NTHREADS, 2) mega_kernel(Params p) {
;     extern __shared__ __attribute__((aligned(16))) char sm[];
amdhsa.kernels:
  - .agpr_count:     0
    .args:
      - .offset:         0
        .size:           176
        .value_kind:     by_value
      - .offset:         176
        .size:           4
        .value_kind:     hidden_block_count_x
      - .offset:         180
        .size:           4
        .value_kind:     hidden_block_count_y
      - .offset:         184
        .size:           4
        .value_kind:     hidden_block_count_z
      - .offset:         188
        .size:           2
        .value_kind:     hidden_group_size_x
      - .offset:         190
        .size:           2
        .value_kind:     hidden_group_size_y
      - .offset:         192
        .size:           2
        .value_kind:     hidden_group_size_z
      - .offset:         194
        .size:           2
        .value_kind:     hidden_remainder_x
      - .offset:         196
        .size:           2
        .value_kind:     hidden_remainder_y
      - .offset:         198
        .size:           2
        .value_kind:     hidden_remainder_z
      - .offset:         216
        .size:           8
        .value_kind:     hidden_global_offset_x
      - .offset:         224
        .size:           8
        .value_kind:     hidden_global_offset_y
      - .offset:         232
        .size:           8
        .value_kind:     hidden_global_offset_z
      - .offset:         240
        .size:           2
        .value_kind:     hidden_grid_dims
      - .offset:         296
        .size:           4
        .value_kind:     hidden_dynamic_lds_size
    .group_segment_fixed_size: 0
    .kernarg_segment_align: 8
    .kernarg_segment_size: 432
    .language:       OpenCL C
    .language_version:
      - 2
      - 0
    .max_flat_workgroup_size: 256
    .name:           _Z11mega_kernel6Params
    .private_segment_fixed_size: 0
    .sgpr_count:     108
    .sgpr_spill_count: 74
    .symbol:         _Z11mega_kernel6Params.kd
    .uniform_work_group_size: 1
    .uses_dynamic_stack: false
    .vgpr_count:     256
    .vgpr_spill_count: 0
    .wavefront_size: 64
